# attention loop: VALU rebalanced across MFMA gaps (<=24 cyc per gap)
# speedup vs baseline: 1.0637x; 1.0060x over previous
; #define ATT_LOAD(t) do { sk0 = *(const u32x4*)(kp0 + (size_t)(t) * 64 * 768); if (has1) sk1 = *(const u32x4*)(kp1 + (size_t)(t) * 64 * 768); sv = *(const u32x4*)(vp + (t) * 64); } while (0)
; #define ATT_STORE(boff) do { *(LAS u32x4*)(lds + (boff) + kw0) = sk0; if (has1) *(LAS u32x4*)(lds + (boff) + kw1) = sk1; *(LAS u32x4*)(lds + (boff) + vw) = sv; } while (0)
; template <bool FIXED> __device__ __forceinline__ void attn_unit(unsigned char* ws, LAS unsigned char* lds, int b, int h, int qb, const int tid, const float sbound) {
;     ...
;     ATT_LOAD(0); ATT_STORE(0); ATT_LOAD(1); ATT_STORE(ABUF); ATT_LOAD(2);
;     __syncthreads();
;     const int pi_r = (r32 & ~12) | ((r32 & 4) << 1) | ((r32 & 8) >> 1);
;     const int kro = pi_r * AKP + hi * 16, vro = AKB + r32 * AVP + hi * 16;
;     f32x16 o0 = {}, o1 = {}, negm = {};
;     float mref = 0.f, lsum = 0.f;
;     ...
;     if constexpr (FIXED) { for (int kt = 0; kt < SEQ / 64; kt += 2) { ATT_STEP_FIXED(pA0, pA1, pB0, pB1, kt); ATT_STEP_FIXED(pB0, pB1, pA0, pA1, kt + 1); }
.Lattn_fx_w0:
	s_or_b64 exec, exec, s[42:43]
	ds_write_b128 v208, v[180:183] offset:58368
	v_exp_f32_e32 v48, v48
	v_exp_f32_e32 v49, v49
	v_exp_f32_e32 v50, v50
	s_waitcnt lgkmcnt(7)
	v_mfma_f32_32x32x16_bf16 v[32:47], v[132:135], v[112:115], v[32:47]
	ds_read_b128 v[128:131], v187 offset:22624
	global_load_dwordx4 v[176:179], v212, s[6:7]
	s_and_saveexec_b64 s[42:43], s[36:37]
	s_cbranch_execz .Lattn_fx_g1
	global_load_dwordx4 v[172:175], v214, s[6:7]
.Lattn_fx_g1:
	s_or_b64 exec, exec, s[42:43]
	global_load_dwordx4 v[180:183], v204, s[40:41]
	s_add_u32 s6, s6, 0x18000
	s_addc_u32 s7, s7, 0
	s_add_u32 s40, s40, 0x80
	s_addc_u32 s41, s41, 0
	v_exp_f32_e32 v51, v51
	v_exp_f32_e32 v52, v52
	v_exp_f32_e32 v53, v53
	s_waitcnt lgkmcnt(7)
	v_mfma_f32_32x32x16_bf16 v[16:31], v[136:139], v[116:119], v[16:31]
	ds_read_b128 v[132:135], v187 offset:22656
	v_exp_f32_e32 v54, v54
	v_exp_f32_e32 v55, v55
	v_cvt_pk_bf16_f32 v120, v48, v49
	v_cvt_pk_bf16_f32 v121, v50, v51
	s_waitcnt lgkmcnt(7)
	v_mfma_f32_32x32x16_bf16 v[32:47], v[140:143], v[116:119], v[32:47]
	ds_read_b128 v[136:139], v187 offset:22688
	v_cvt_pk_bf16_f32 v122, v52, v53
	v_cvt_pk_bf16_f32 v123, v54, v55
	v_exp_f32_e32 v56, v56
	v_exp_f32_e32 v57, v57
	s_waitcnt lgkmcnt(7)
	v_mfma_f32_32x32x16_bf16 v[96:111], v[188:191], v[164:167], v[0:15]
	ds_read_b128 v[140:143], v209 offset:13376
	v_exp_f32_e32 v58, v58
	v_exp_f32_e32 v59, v59
	v_add_f32_e32 v48, v64, v48
	v_add_f32_e32 v244, v244, v48
	s_waitcnt lgkmcnt(7)
	v_mfma_f32_32x32x16_bf16 v[96:111], v[168:171], v[144:147], v[96:111]
	ds_read_b128 v[188:191], v209 offset:17984
	v_exp_f32_e32 v60, v60
	v_exp_f32_e32 v61, v61
	v_add_f32_e32 v49, v65, v49
	v_add_f32_e32 v245, v245, v49
	s_waitcnt lgkmcnt(7)
	v_mfma_f32_32x32x16_bf16 v[96:111], v[220:223], v[148:151], v[96:111]
	ds_read_b128 v[168:171], v187 offset:29184
	v_exp_f32_e32 v62, v62
	v_exp_f32_e32 v63, v63
	v_add_f32_e32 v50, v66, v50
	v_add_f32_e32 v242, v242, v50
	s_waitcnt lgkmcnt(5)
	v_mfma_f32_32x32x16_bf16 v[96:111], v[128:131], v[152:155], v[96:111]
	ds_read_b128 v[220:223], v187 offset:29216
	v_cvt_pk_bf16_f32 v124, v56, v57
	v_cvt_pk_bf16_f32 v125, v58, v59
	v_cvt_pk_bf16_f32 v126, v60, v61
	v_cvt_pk_bf16_f32 v127, v62, v63
	v_add_f32_e32 v51, v67, v51
	v_add_f32_e32 v243, v243, v51
	s_waitcnt lgkmcnt(5)
	v_mfma_f32_32x32x16_bf16 v[96:111], v[132:135], v[156:159], v[96:111]
	ds_read_b128 v[128:131], v187 offset:29248
	v_add_f32_e32 v52, v68, v52
	v_add_f32_e32 v240, v240, v52
	v_add_f32_e32 v53, v69, v53
	v_add_f32_e32 v241, v241, v53
	v_add_f32_e32 v54, v70, v54
	v_add_f32_e32 v238, v238, v54
	s_waitcnt lgkmcnt(5)
	v_mfma_f32_32x32x16_bf16 v[96:111], v[136:139], v[160:163], v[96:111]
	ds_read_b128 v[132:135], v209 offset:13408
	v_add_f32_e32 v55, v71, v55
	v_add_f32_e32 v239, v239, v55
	v_add_f32_e32 v56, v72, v56
	v_add_f32_e32 v236, v236, v56
	v_add_f32_e32 v57, v73, v57
	v_add_f32_e32 v237, v237, v57
	s_waitcnt lgkmcnt(5)
	v_mfma_f32_32x32x16_bf16 v[16:31], v[140:143], v[120:123], v[16:31]
	ds_read_b128 v[136:139], v209 offset:18016
	v_add_f32_e32 v58, v74, v58
	v_add_f32_e32 v234, v234, v58
	v_add_f32_e32 v59, v75, v59
	v_add_f32_e32 v235, v235, v59
	v_add_f32_e32 v60, v76, v60
	v_add_f32_e32 v232, v232, v60
	s_waitcnt lgkmcnt(5)
	v_mfma_f32_32x32x16_bf16 v[32:47], v[188:191], v[120:123], v[32:47]
	ds_read_b128 v[140:143], v187 offset:29280
	v_add_f32_e32 v61, v77, v61
	v_add_f32_e32 v233, v233, v61
	v_add_f32_e32 v62, v78, v62
	v_add_f32_e32 v230, v230, v62
	s_waitcnt lgkmcnt(5)
	v_mfma_f32_32x32x16_bf16 v[80:95], v[168:171], v[164:167], v[0:15]
	ds_read_b128 v[188:191], v187 offset:29312
	v_exp_f32_e32 v96, v96
	v_exp_f32_e32 v97, v97
	v_exp_f32_e32 v98, v98
	s_waitcnt lgkmcnt(5)
	v_mfma_f32_32x32x16_bf16 v[80:95], v[220:223], v[144:147], v[80:95]
	ds_read_b128 v[168:171], v187 offset:29344
	v_exp_f32_e32 v99, v99
	v_exp_f32_e32 v100, v100
	v_exp_f32_e32 v101, v101
	s_waitcnt lgkmcnt(5)
	v_mfma_f32_32x32x16_bf16 v[80:95], v[128:131], v[148:151], v[80:95]
	ds_read_b128 v[128:131], v209 offset:35840
	v_exp_f32_e32 v102, v102
	v_exp_f32_e32 v103, v103
	v_cvt_pk_bf16_f32 v112, v96, v97
	v_cvt_pk_bf16_f32 v113, v98, v99
	s_waitcnt lgkmcnt(5)
	v_mfma_f32_32x32x16_bf16 v[16:31], v[132:135], v[124:127], v[16:31]
	ds_read_b128 v[132:135], v209 offset:40448
	v_cvt_pk_bf16_f32 v114, v100, v101
	v_cvt_pk_bf16_f32 v115, v102, v103
	v_exp_f32_e32 v104, v104
	v_exp_f32_e32 v105, v105
	s_waitcnt lgkmcnt(5)
	v_mfma_f32_32x32x16_bf16 v[32:47], v[136:139], v[124:127], v[32:47]
	ds_read_b128 v[136:139], v209 offset:35872
	v_exp_f32_e32 v106, v106
	v_exp_f32_e32 v107, v107
	v_exp_f32_e32 v108, v108
	s_waitcnt lgkmcnt(5)
	v_mfma_f32_32x32x16_bf16 v[80:95], v[140:143], v[152:155], v[80:95]
	ds_read_b128 v[140:143], v209 offset:40480
	v_exp_f32_e32 v109, v109
	v_exp_f32_e32 v110, v110
	v_exp_f32_e32 v111, v111
	s_waitcnt lgkmcnt(5)
	v_mfma_f32_32x32x16_bf16 v[80:95], v[188:191], v[156:159], v[80:95]
	v_cvt_pk_bf16_f32 v116, v104, v105
	v_cvt_pk_bf16_f32 v117, v106, v107
	v_cvt_pk_bf16_f32 v118, v108, v109
	v_cvt_pk_bf16_f32 v119, v110, v111
	s_waitcnt lgkmcnt(4)
	v_mfma_f32_32x32x16_bf16 v[80:95], v[168:171], v[160:163], v[80:95]
	v_add_f32_e32 v63, v79, v63
	v_add_f32_e32 v231, v231, v63
	s_waitcnt lgkmcnt(4)
	s_barrier
	ds_read_b128 v[188:191], v187 offset:45056
	ds_read_b128 v[168:171], v187 offset:45088
	s_waitcnt lgkmcnt(5)
	v_mfma_f32_32x32x16_bf16 v[16:31], v[128:131], v[112:115], v[16:31]
	ds_read_b128 v[220:223], v187 offset:45120
	s_waitcnt vmcnt(0)
	ds_write_b128 v211, v[176:179] offset:0
	s_and_saveexec_b64 s[42:43], s[36:37]
	s_cbranch_execz .Lattn_fx_w2
	ds_write_b128 v186, v[172:175] offset:0
; #define ATT_LOAD(t) do { sk0 = *(const u32x4*)(kp0 + (size_t)(t) * 64 * 768); if (has1) sk1 = *(const u32x4*)(kp1 + (size_t)(t) * 64 * 768); sv = *(const u32x4*)(vp + (t) * 64); } while (0)
; #define ATT_STORE(boff) do { *(LAS u32x4*)(lds + (boff) + kw0) = sk0; if (has1) *(LAS u32x4*)(lds + (boff) + kw1) = sk1; *(LAS u32x4*)(lds + (boff) + vw) = sv; } while (0)
; template <bool FIXED> __device__ __forceinline__ void attn_unit(unsigned char* ws, LAS unsigned char* lds, int b, int h, int qb, const int tid, const float sbound) {
;     ...
;     ATT_LOAD(0); ATT_STORE(0); ATT_LOAD(1); ATT_STORE(ABUF); ATT_LOAD(2);
;     __syncthreads();
;     const int pi_r = (r32 & ~12) | ((r32 & 4) << 1) | ((r32 & 8) >> 1);
;     const int kro = pi_r * AKP + hi * 16, vro = AKB + r32 * AVP + hi * 16;
;     f32x16 o0 = {}, o1 = {}, negm = {};
;     float mref = 0.f, lsum = 0.f;
;     ...
;     if constexpr (FIXED) { for (int kt = 0; kt < SEQ / 64; kt += 2) { ATT_STEP_FIXED(pA0, pA1, pB0, pB1, kt); ATT_STEP_FIXED(pB0, pB1, pA0, pA1, kt + 1); }
.Lattn_fx_w2:
	s_or_b64 exec, exec, s[42:43]
	ds_write_b128 v208, v[180:183] offset:13312
	v_exp_f32_e32 v80, v80
	v_exp_f32_e32 v81, v81
	v_exp_f32_e32 v82, v82
	s_waitcnt lgkmcnt(7)
	v_mfma_f32_32x32x16_bf16 v[32:47], v[132:135], v[112:115], v[32:47]
	ds_read_b128 v[128:131], v187 offset:45152
	global_load_dwordx4 v[176:179], v212, s[6:7]
	s_and_saveexec_b64 s[42:43], s[36:37]
	s_cbranch_execz .Lattn_fx_g3
	global_load_dwordx4 v[172:175], v214, s[6:7]
.Lattn_fx_g3:
	s_or_b64 exec, exec, s[42:43]
	global_load_dwordx4 v[180:183], v204, s[40:41]
	s_add_u32 s6, s6, 0x18000
	s_addc_u32 s7, s7, 0
	s_add_u32 s40, s40, 0x80
	s_addc_u32 s41, s41, 0
	v_exp_f32_e32 v83, v83
	v_exp_f32_e32 v84, v84
	v_exp_f32_e32 v85, v85
	s_waitcnt lgkmcnt(7)
	v_mfma_f32_32x32x16_bf16 v[16:31], v[136:139], v[116:119], v[16:31]
	ds_read_b128 v[132:135], v187 offset:45184
	v_exp_f32_e32 v86, v86
	v_exp_f32_e32 v87, v87
	v_cvt_pk_bf16_f32 v120, v80, v81
	v_cvt_pk_bf16_f32 v121, v82, v83
	s_waitcnt lgkmcnt(7)
	v_mfma_f32_32x32x16_bf16 v[32:47], v[140:143], v[116:119], v[32:47]
	ds_read_b128 v[136:139], v187 offset:45216
	v_cvt_pk_bf16_f32 v122, v84, v85
	v_cvt_pk_bf16_f32 v123, v86, v87
	v_exp_f32_e32 v88, v88
	v_exp_f32_e32 v89, v89
	s_waitcnt lgkmcnt(7)
	v_mfma_f32_32x32x16_bf16 v[64:79], v[188:191], v[164:167], v[0:15]
	ds_read_b128 v[140:143], v209 offset:35904
	v_exp_f32_e32 v90, v90
	v_exp_f32_e32 v91, v91
	v_add_f32_e32 v80, v96, v80
	v_add_f32_e32 v244, v244, v80
	s_waitcnt lgkmcnt(7)
	v_mfma_f32_32x32x16_bf16 v[64:79], v[168:171], v[144:147], v[64:79]
	ds_read_b128 v[188:191], v209 offset:40512
	v_exp_f32_e32 v92, v92
	v_exp_f32_e32 v93, v93
	v_add_f32_e32 v81, v97, v81
	v_add_f32_e32 v245, v245, v81
	s_waitcnt lgkmcnt(7)
	v_mfma_f32_32x32x16_bf16 v[64:79], v[220:223], v[148:151], v[64:79]
	ds_read_b128 v[168:171], v187 offset:51712
	v_exp_f32_e32 v94, v94
	v_exp_f32_e32 v95, v95
	v_add_f32_e32 v82, v98, v82
	v_add_f32_e32 v242, v242, v82
	s_waitcnt lgkmcnt(5)
	v_mfma_f32_32x32x16_bf16 v[64:79], v[128:131], v[152:155], v[64:79]
	ds_read_b128 v[220:223], v187 offset:51744
	v_cvt_pk_bf16_f32 v124, v88, v89
	v_cvt_pk_bf16_f32 v125, v90, v91
	v_cvt_pk_bf16_f32 v126, v92, v93
	v_cvt_pk_bf16_f32 v127, v94, v95
	v_add_f32_e32 v83, v99, v83
	v_add_f32_e32 v243, v243, v83
	s_waitcnt lgkmcnt(5)
	v_mfma_f32_32x32x16_bf16 v[64:79], v[132:135], v[156:159], v[64:79]
	ds_read_b128 v[128:131], v187 offset:51776
	v_add_f32_e32 v84, v100, v84
	v_add_f32_e32 v240, v240, v84
	v_add_f32_e32 v85, v101, v85
	v_add_f32_e32 v241, v241, v85
	v_add_f32_e32 v86, v102, v86
	v_add_f32_e32 v238, v238, v86
	s_waitcnt lgkmcnt(5)
	v_mfma_f32_32x32x16_bf16 v[64:79], v[136:139], v[160:163], v[64:79]
	ds_read_b128 v[132:135], v209 offset:35936
	v_add_f32_e32 v87, v103, v87
	v_add_f32_e32 v239, v239, v87
	v_add_f32_e32 v88, v104, v88
	v_add_f32_e32 v236, v236, v88
	v_add_f32_e32 v89, v105, v89
	v_add_f32_e32 v237, v237, v89
	s_waitcnt lgkmcnt(5)
	v_mfma_f32_32x32x16_bf16 v[16:31], v[140:143], v[120:123], v[16:31]
	ds_read_b128 v[136:139], v209 offset:40544
	v_add_f32_e32 v90, v106, v90
	v_add_f32_e32 v234, v234, v90
	v_add_f32_e32 v91, v107, v91
	v_add_f32_e32 v235, v235, v91
	v_add_f32_e32 v92, v108, v92
	v_add_f32_e32 v232, v232, v92
	s_waitcnt lgkmcnt(5)
	v_mfma_f32_32x32x16_bf16 v[32:47], v[188:191], v[120:123], v[32:47]
	ds_read_b128 v[140:143], v187 offset:51808
	v_add_f32_e32 v93, v109, v93
	v_add_f32_e32 v233, v233, v93
	v_add_f32_e32 v94, v110, v94
	v_add_f32_e32 v230, v230, v94
	s_waitcnt lgkmcnt(5)
	v_mfma_f32_32x32x16_bf16 v[48:63], v[168:171], v[164:167], v[0:15]
	ds_read_b128 v[188:191], v187 offset:51840
	v_exp_f32_e32 v64, v64
	v_exp_f32_e32 v65, v65
	v_exp_f32_e32 v66, v66
	s_waitcnt lgkmcnt(5)
	v_mfma_f32_32x32x16_bf16 v[48:63], v[220:223], v[144:147], v[48:63]
	ds_read_b128 v[168:171], v187 offset:51872
	v_exp_f32_e32 v67, v67
	v_exp_f32_e32 v68, v68
	v_exp_f32_e32 v69, v69
	s_waitcnt lgkmcnt(5)
	v_mfma_f32_32x32x16_bf16 v[48:63], v[128:131], v[148:151], v[48:63]
	ds_read_b128 v[128:131], v209 offset:58368
	v_exp_f32_e32 v70, v70
	v_exp_f32_e32 v71, v71
	v_cvt_pk_bf16_f32 v112, v64, v65
	v_cvt_pk_bf16_f32 v113, v66, v67
	s_waitcnt lgkmcnt(5)
	v_mfma_f32_32x32x16_bf16 v[16:31], v[132:135], v[124:127], v[16:31]
	ds_read_b128 v[132:135], v209 offset:62976
	v_cvt_pk_bf16_f32 v114, v68, v69
	v_cvt_pk_bf16_f32 v115, v70, v71
	v_exp_f32_e32 v72, v72
	v_exp_f32_e32 v73, v73
	s_waitcnt lgkmcnt(5)
	v_mfma_f32_32x32x16_bf16 v[32:47], v[136:139], v[124:127], v[32:47]
	ds_read_b128 v[136:139], v209 offset:58400
	v_exp_f32_e32 v74, v74
	v_exp_f32_e32 v75, v75
	v_exp_f32_e32 v76, v76
	s_waitcnt lgkmcnt(5)
	v_mfma_f32_32x32x16_bf16 v[48:63], v[140:143], v[152:155], v[48:63]
	ds_read_b128 v[140:143], v209 offset:63008
	v_exp_f32_e32 v77, v77
	v_exp_f32_e32 v78, v78
	v_exp_f32_e32 v79, v79
	s_waitcnt lgkmcnt(5)
	v_mfma_f32_32x32x16_bf16 v[48:63], v[188:191], v[156:159], v[48:63]
	v_cvt_pk_bf16_f32 v116, v72, v73
	v_cvt_pk_bf16_f32 v117, v74, v75
	v_cvt_pk_bf16_f32 v118, v76, v77
	v_cvt_pk_bf16_f32 v119, v78, v79
	s_waitcnt lgkmcnt(4)
	v_mfma_f32_32x32x16_bf16 v[48:63], v[168:171], v[160:163], v[48:63]
	v_add_f32_e32 v95, v111, v95
	v_add_f32_e32 v231, v231, v95
	s_waitcnt lgkmcnt(4)
	s_barrier
	ds_read_b128 v[188:191], v187 offset:0
	ds_read_b128 v[168:171], v187 offset:32
	s_waitcnt lgkmcnt(5)
	v_mfma_f32_32x32x16_bf16 v[16:31], v[128:131], v[112:115], v[16:31]
	ds_read_b128 v[220:223], v187 offset:64
	s_waitcnt vmcnt(0)
	ds_write_b128 v211, v[176:179] offset:22528
	s_and_saveexec_b64 s[42:43], s[36:37]
	s_cbranch_execz .Lattn_fx_w4
	ds_write_b128 v186, v[172:175] offset:22528
; #define ATT_LOAD(t) do { sk0 = *(const u32x4*)(kp0 + (size_t)(t) * 64 * 768); if (has1) sk1 = *(const u32x4*)(kp1 + (size_t)(t) * 64 * 768); sv = *(const u32x4*)(vp + (t) * 64); } while (0)
; #define ATT_STORE(boff) do { *(LAS u32x4*)(lds + (boff) + kw0) = sk0; if (has1) *(LAS u32x4*)(lds + (boff) + kw1) = sk1; *(LAS u32x4*)(lds + (boff) + vw) = sv; } while (0)
; template <bool FIXED> __device__ __forceinline__ void attn_unit(unsigned char* ws, LAS unsigned char* lds, int b, int h, int qb, const int tid, const float sbound) {
;     ...
;     ATT_LOAD(0); ATT_STORE(0); ATT_LOAD(1); ATT_STORE(ABUF); ATT_LOAD(2);
;     __syncthreads();
;     const int pi_r = (r32 & ~12) | ((r32 & 4) << 1) | ((r32 & 8) >> 1);
;     const int kro = pi_r * AKP + hi * 16, vro = AKB + r32 * AVP + hi * 16;
;     f32x16 o0 = {}, o1 = {}, negm = {};
;     float mref = 0.f, lsum = 0.f;
;     ...
;     if constexpr (FIXED) { for (int kt = 0; kt < SEQ / 64; kt += 2) { ATT_STEP_FIXED(pA0, pA1, pB0, pB1, kt); ATT_STEP_FIXED(pB0, pB1, pA0, pA1, kt + 1); }
.Lattn_fx_w4:
	s_or_b64 exec, exec, s[42:43]
	ds_write_b128 v208, v[180:183] offset:35840
	v_exp_f32_e32 v48, v48
	v_exp_f32_e32 v49, v49
	v_exp_f32_e32 v50, v50
	s_waitcnt lgkmcnt(7)
	v_mfma_f32_32x32x16_bf16 v[32:47], v[132:135], v[112:115], v[32:47]
	ds_read_b128 v[128:131], v187 offset:96
	global_load_dwordx4 v[176:179], v212, s[6:7]
	s_and_saveexec_b64 s[42:43], s[36:37]
	s_cbranch_execz .Lattn_fx_g5
	global_load_dwordx4 v[172:175], v214, s[6:7]
.Lattn_fx_g5:
	s_or_b64 exec, exec, s[42:43]
	global_load_dwordx4 v[180:183], v204, s[40:41]
	s_add_u32 s6, s6, 0x18000
	s_addc_u32 s7, s7, 0
	s_add_u32 s40, s40, 0x80
	s_addc_u32 s41, s41, 0
	v_exp_f32_e32 v51, v51
	v_exp_f32_e32 v52, v52
	v_exp_f32_e32 v53, v53
	s_waitcnt lgkmcnt(7)
	v_mfma_f32_32x32x16_bf16 v[16:31], v[136:139], v[116:119], v[16:31]
	ds_read_b128 v[132:135], v187 offset:128
	v_exp_f32_e32 v54, v54
	v_exp_f32_e32 v55, v55
	v_cvt_pk_bf16_f32 v120, v48, v49
	v_cvt_pk_bf16_f32 v121, v50, v51
	s_waitcnt lgkmcnt(7)
	v_mfma_f32_32x32x16_bf16 v[32:47], v[140:143], v[116:119], v[32:47]
	ds_read_b128 v[136:139], v187 offset:160
	v_cvt_pk_bf16_f32 v122, v52, v53
	v_cvt_pk_bf16_f32 v123, v54, v55
	v_exp_f32_e32 v56, v56
	v_exp_f32_e32 v57, v57
	s_waitcnt lgkmcnt(7)
	v_mfma_f32_32x32x16_bf16 v[96:111], v[188:191], v[164:167], v[0:15]
	ds_read_b128 v[140:143], v209 offset:58432
	v_exp_f32_e32 v58, v58
	v_exp_f32_e32 v59, v59
	v_add_f32_e32 v48, v64, v48
	v_add_f32_e32 v244, v244, v48
	s_waitcnt lgkmcnt(7)
	v_mfma_f32_32x32x16_bf16 v[96:111], v[168:171], v[144:147], v[96:111]
	ds_read_b128 v[188:191], v209 offset:63040
	v_exp_f32_e32 v60, v60
	v_exp_f32_e32 v61, v61
	v_add_f32_e32 v49, v65, v49
	v_add_f32_e32 v245, v245, v49
	s_waitcnt lgkmcnt(7)
	v_mfma_f32_32x32x16_bf16 v[96:111], v[220:223], v[148:151], v[96:111]
	ds_read_b128 v[168:171], v187 offset:6656
	v_exp_f32_e32 v62, v62
	v_exp_f32_e32 v63, v63
	v_add_f32_e32 v50, v66, v50
	v_add_f32_e32 v242, v242, v50
	s_waitcnt lgkmcnt(5)
	v_mfma_f32_32x32x16_bf16 v[96:111], v[128:131], v[152:155], v[96:111]
	ds_read_b128 v[220:223], v187 offset:6688
	v_cvt_pk_bf16_f32 v124, v56, v57
	v_cvt_pk_bf16_f32 v125, v58, v59
	v_cvt_pk_bf16_f32 v126, v60, v61
	v_cvt_pk_bf16_f32 v127, v62, v63
	v_add_f32_e32 v51, v67, v51
	v_add_f32_e32 v243, v243, v51
	s_waitcnt lgkmcnt(5)
	v_mfma_f32_32x32x16_bf16 v[96:111], v[132:135], v[156:159], v[96:111]
	ds_read_b128 v[128:131], v187 offset:6720
	v_add_f32_e32 v52, v68, v52
	v_add_f32_e32 v240, v240, v52
	v_add_f32_e32 v53, v69, v53
	v_add_f32_e32 v241, v241, v53
	v_add_f32_e32 v54, v70, v54
	v_add_f32_e32 v238, v238, v54
	s_waitcnt lgkmcnt(5)
	v_mfma_f32_32x32x16_bf16 v[96:111], v[136:139], v[160:163], v[96:111]
	ds_read_b128 v[132:135], v209 offset:58464
	v_add_f32_e32 v55, v71, v55
	v_add_f32_e32 v239, v239, v55
	v_add_f32_e32 v56, v72, v56
	v_add_f32_e32 v236, v236, v56
	v_add_f32_e32 v57, v73, v57
	v_add_f32_e32 v237, v237, v57
	s_waitcnt lgkmcnt(5)
	v_mfma_f32_32x32x16_bf16 v[16:31], v[140:143], v[120:123], v[16:31]
	ds_read_b128 v[136:139], v209 offset:63072
	v_add_f32_e32 v58, v74, v58
	v_add_f32_e32 v234, v234, v58
	v_add_f32_e32 v59, v75, v59
	v_add_f32_e32 v235, v235, v59
	v_add_f32_e32 v60, v76, v60
	v_add_f32_e32 v232, v232, v60
	s_waitcnt lgkmcnt(5)
	v_mfma_f32_32x32x16_bf16 v[32:47], v[188:191], v[120:123], v[32:47]
	ds_read_b128 v[140:143], v187 offset:6752
	v_add_f32_e32 v61, v77, v61
	v_add_f32_e32 v233, v233, v61
	v_add_f32_e32 v62, v78, v62
	v_add_f32_e32 v230, v230, v62
	s_waitcnt lgkmcnt(5)
	v_mfma_f32_32x32x16_bf16 v[80:95], v[168:171], v[164:167], v[0:15]
	ds_read_b128 v[188:191], v187 offset:6784
	v_exp_f32_e32 v96, v96
	v_exp_f32_e32 v97, v97
	v_exp_f32_e32 v98, v98
	s_waitcnt lgkmcnt(5)
	v_mfma_f32_32x32x16_bf16 v[80:95], v[220:223], v[144:147], v[80:95]
	ds_read_b128 v[168:171], v187 offset:6816
	v_exp_f32_e32 v99, v99
	v_exp_f32_e32 v100, v100
	v_exp_f32_e32 v101, v101
	s_waitcnt lgkmcnt(5)
	v_mfma_f32_32x32x16_bf16 v[80:95], v[128:131], v[148:151], v[80:95]
	ds_read_b128 v[128:131], v209 offset:13312
	v_exp_f32_e32 v102, v102
	v_exp_f32_e32 v103, v103
	v_cvt_pk_bf16_f32 v112, v96, v97
	v_cvt_pk_bf16_f32 v113, v98, v99
	s_waitcnt lgkmcnt(5)
	v_mfma_f32_32x32x16_bf16 v[16:31], v[132:135], v[124:127], v[16:31]
	ds_read_b128 v[132:135], v209 offset:17920
	v_cvt_pk_bf16_f32 v114, v100, v101
	v_cvt_pk_bf16_f32 v115, v102, v103
	v_exp_f32_e32 v104, v104
	v_exp_f32_e32 v105, v105
	s_waitcnt lgkmcnt(5)
	v_mfma_f32_32x32x16_bf16 v[32:47], v[136:139], v[124:127], v[32:47]
	ds_read_b128 v[136:139], v209 offset:13344
	v_exp_f32_e32 v106, v106
	v_exp_f32_e32 v107, v107
	v_exp_f32_e32 v108, v108
	s_waitcnt lgkmcnt(5)
	v_mfma_f32_32x32x16_bf16 v[80:95], v[140:143], v[152:155], v[80:95]
	ds_read_b128 v[140:143], v209 offset:17952
	v_exp_f32_e32 v109, v109
	v_exp_f32_e32 v110, v110
	v_exp_f32_e32 v111, v111
	s_waitcnt lgkmcnt(5)
	v_mfma_f32_32x32x16_bf16 v[80:95], v[188:191], v[156:159], v[80:95]
	v_cvt_pk_bf16_f32 v116, v104, v105
	v_cvt_pk_bf16_f32 v117, v106, v107
	v_cvt_pk_bf16_f32 v118, v108, v109
	v_cvt_pk_bf16_f32 v119, v110, v111
	s_waitcnt lgkmcnt(4)
	v_mfma_f32_32x32x16_bf16 v[80:95], v[168:171], v[160:163], v[80:95]
	v_add_f32_e32 v63, v79, v63
	v_add_f32_e32 v231, v231, v63
	s_waitcnt lgkmcnt(4)
	s_barrier
	ds_read_b128 v[188:191], v187 offset:22528
	ds_read_b128 v[168:171], v187 offset:22560
	s_waitcnt lgkmcnt(5)
	v_mfma_f32_32x32x16_bf16 v[16:31], v[128:131], v[112:115], v[16:31]
	ds_read_b128 v[220:223], v187 offset:22592
	s_waitcnt vmcnt(0)
	ds_write_b128 v211, v[176:179] offset:45056
	s_and_saveexec_b64 s[42:43], s[36:37]
	s_cbranch_execz .Lattn_fx_w6
	ds_write_b128 v186, v[172:175] offset:45056
; #define ATT_LOAD(t) do { sk0 = *(const u32x4*)(kp0 + (size_t)(t) * 64 * 768); if (has1) sk1 = *(const u32x4*)(kp1 + (size_t)(t) * 64 * 768); sv = *(const u32x4*)(vp + (t) * 64); } while (0)
; #define ATT_STORE(boff) do { *(LAS u32x4*)(lds + (boff) + kw0) = sk0; if (has1) *(LAS u32x4*)(lds + (boff) + kw1) = sk1; *(LAS u32x4*)(lds + (boff) + vw) = sv; } while (0)
; template <bool FIXED> __device__ __forceinline__ void attn_unit(unsigned char* ws, LAS unsigned char* lds, int b, int h, int qb, const int tid, const float sbound) {
;     ...
;     ATT_LOAD(0); ATT_STORE(0); ATT_LOAD(1); ATT_STORE(ABUF); ATT_LOAD(2);
;     __syncthreads();
;     const int pi_r = (r32 & ~12) | ((r32 & 4) << 1) | ((r32 & 8) >> 1);
;     const int kro = pi_r * AKP + hi * 16, vro = AKB + r32 * AVP + hi * 16;
;     f32x16 o0 = {}, o1 = {}, negm = {};
;     float mref = 0.f, lsum = 0.f;
;     ...
;     if constexpr (FIXED) { for (int kt = 0; kt < SEQ / 64; kt += 2) { ATT_STEP_FIXED(pA0, pA1, pB0, pB1, kt); ATT_STEP_FIXED(pB0, pB1, pA0, pA1, kt + 1); }
.Lattn_fx_w6:
	s_or_b64 exec, exec, s[42:43]
	ds_write_b128 v208, v[180:183] offset:58368
	v_exp_f32_e32 v80, v80
	v_exp_f32_e32 v81, v81
	v_exp_f32_e32 v82, v82
	s_waitcnt lgkmcnt(7)
	v_mfma_f32_32x32x16_bf16 v[32:47], v[132:135], v[112:115], v[32:47]
	ds_read_b128 v[128:131], v187 offset:22624
	global_load_dwordx4 v[176:179], v212, s[6:7]
	s_and_saveexec_b64 s[42:43], s[36:37]
	s_cbranch_execz .Lattn_fx_g7
	global_load_dwordx4 v[172:175], v214, s[6:7]
.Lattn_fx_g7:
	s_or_b64 exec, exec, s[42:43]
	global_load_dwordx4 v[180:183], v204, s[40:41]
	s_add_u32 s6, s6, 0x18000
	s_addc_u32 s7, s7, 0
	s_add_u32 s40, s40, 0x80
	s_addc_u32 s41, s41, 0
	v_exp_f32_e32 v83, v83
	v_exp_f32_e32 v84, v84
	v_exp_f32_e32 v85, v85
	s_waitcnt lgkmcnt(7)
	v_mfma_f32_32x32x16_bf16 v[16:31], v[136:139], v[116:119], v[16:31]
	ds_read_b128 v[132:135], v187 offset:22656
	v_exp_f32_e32 v86, v86
	v_exp_f32_e32 v87, v87
	v_cvt_pk_bf16_f32 v120, v80, v81
	v_cvt_pk_bf16_f32 v121, v82, v83
	s_waitcnt lgkmcnt(7)
	v_mfma_f32_32x32x16_bf16 v[32:47], v[140:143], v[116:119], v[32:47]
	ds_read_b128 v[136:139], v187 offset:22688
	v_cvt_pk_bf16_f32 v122, v84, v85
	v_cvt_pk_bf16_f32 v123, v86, v87
	v_exp_f32_e32 v88, v88
	v_exp_f32_e32 v89, v89
	s_waitcnt lgkmcnt(7)
	v_mfma_f32_32x32x16_bf16 v[64:79], v[188:191], v[164:167], v[0:15]
	ds_read_b128 v[140:143], v209 offset:13376
	v_exp_f32_e32 v90, v90
	v_exp_f32_e32 v91, v91
	v_add_f32_e32 v80, v96, v80
	v_add_f32_e32 v244, v244, v80
	s_waitcnt lgkmcnt(7)
	v_mfma_f32_32x32x16_bf16 v[64:79], v[168:171], v[144:147], v[64:79]
	ds_read_b128 v[188:191], v209 offset:17984
	v_exp_f32_e32 v92, v92
	v_exp_f32_e32 v93, v93
	v_add_f32_e32 v81, v97, v81
	v_add_f32_e32 v245, v245, v81
	s_waitcnt lgkmcnt(7)
	v_mfma_f32_32x32x16_bf16 v[64:79], v[220:223], v[148:151], v[64:79]
	ds_read_b128 v[168:171], v187 offset:29184
	v_exp_f32_e32 v94, v94
	v_exp_f32_e32 v95, v95
	v_add_f32_e32 v82, v98, v82
	v_add_f32_e32 v242, v242, v82
	s_waitcnt lgkmcnt(5)
	v_mfma_f32_32x32x16_bf16 v[64:79], v[128:131], v[152:155], v[64:79]
	ds_read_b128 v[220:223], v187 offset:29216
	v_cvt_pk_bf16_f32 v124, v88, v89
	v_cvt_pk_bf16_f32 v125, v90, v91
	v_cvt_pk_bf16_f32 v126, v92, v93
	v_cvt_pk_bf16_f32 v127, v94, v95
	v_add_f32_e32 v83, v99, v83
	v_add_f32_e32 v243, v243, v83
	s_waitcnt lgkmcnt(5)
	v_mfma_f32_32x32x16_bf16 v[64:79], v[132:135], v[156:159], v[64:79]
	ds_read_b128 v[128:131], v187 offset:29248
	v_add_f32_e32 v84, v100, v84
	v_add_f32_e32 v240, v240, v84
	v_add_f32_e32 v85, v101, v85
	v_add_f32_e32 v241, v241, v85
	v_add_f32_e32 v86, v102, v86
	v_add_f32_e32 v238, v238, v86
	s_waitcnt lgkmcnt(5)
	v_mfma_f32_32x32x16_bf16 v[64:79], v[136:139], v[160:163], v[64:79]
	ds_read_b128 v[132:135], v209 offset:13408
	v_add_f32_e32 v87, v103, v87
	v_add_f32_e32 v239, v239, v87
	v_add_f32_e32 v88, v104, v88
	v_add_f32_e32 v236, v236, v88
	v_add_f32_e32 v89, v105, v89
	v_add_f32_e32 v237, v237, v89
	s_waitcnt lgkmcnt(5)
	v_mfma_f32_32x32x16_bf16 v[16:31], v[140:143], v[120:123], v[16:31]
	ds_read_b128 v[136:139], v209 offset:18016
	v_add_f32_e32 v90, v106, v90
	v_add_f32_e32 v234, v234, v90
	v_add_f32_e32 v91, v107, v91
	v_add_f32_e32 v235, v235, v91
	v_add_f32_e32 v92, v108, v92
	v_add_f32_e32 v232, v232, v92
	s_waitcnt lgkmcnt(5)
	v_mfma_f32_32x32x16_bf16 v[32:47], v[188:191], v[120:123], v[32:47]
	ds_read_b128 v[140:143], v187 offset:29280
	v_add_f32_e32 v93, v109, v93
	v_add_f32_e32 v233, v233, v93
	v_add_f32_e32 v94, v110, v94
	v_add_f32_e32 v230, v230, v94
	s_waitcnt lgkmcnt(5)
	v_mfma_f32_32x32x16_bf16 v[48:63], v[168:171], v[164:167], v[0:15]
	ds_read_b128 v[188:191], v187 offset:29312
	v_exp_f32_e32 v64, v64
	v_exp_f32_e32 v65, v65
	v_exp_f32_e32 v66, v66
	s_waitcnt lgkmcnt(5)
	v_mfma_f32_32x32x16_bf16 v[48:63], v[220:223], v[144:147], v[48:63]
	ds_read_b128 v[168:171], v187 offset:29344
	v_exp_f32_e32 v67, v67
	v_exp_f32_e32 v68, v68
	v_exp_f32_e32 v69, v69
	s_waitcnt lgkmcnt(5)
	v_mfma_f32_32x32x16_bf16 v[48:63], v[128:131], v[148:151], v[48:63]
	ds_read_b128 v[128:131], v209 offset:35840
	v_exp_f32_e32 v70, v70
	v_exp_f32_e32 v71, v71
	v_cvt_pk_bf16_f32 v112, v64, v65
	v_cvt_pk_bf16_f32 v113, v66, v67
	s_waitcnt lgkmcnt(5)
	v_mfma_f32_32x32x16_bf16 v[16:31], v[132:135], v[124:127], v[16:31]
	ds_read_b128 v[132:135], v209 offset:40448
	v_cvt_pk_bf16_f32 v114, v68, v69
	v_cvt_pk_bf16_f32 v115, v70, v71
	v_exp_f32_e32 v72, v72
	v_exp_f32_e32 v73, v73
	s_waitcnt lgkmcnt(5)
	v_mfma_f32_32x32x16_bf16 v[32:47], v[136:139], v[124:127], v[32:47]
	ds_read_b128 v[136:139], v209 offset:35872
	v_exp_f32_e32 v74, v74
	v_exp_f32_e32 v75, v75
	v_exp_f32_e32 v76, v76
	s_waitcnt lgkmcnt(5)
	v_mfma_f32_32x32x16_bf16 v[48:63], v[140:143], v[152:155], v[48:63]
	ds_read_b128 v[140:143], v209 offset:40480
	v_exp_f32_e32 v77, v77
	v_exp_f32_e32 v78, v78
	v_exp_f32_e32 v79, v79
	s_waitcnt lgkmcnt(5)
	v_mfma_f32_32x32x16_bf16 v[48:63], v[188:191], v[156:159], v[48:63]
	v_cvt_pk_bf16_f32 v116, v72, v73
	v_cvt_pk_bf16_f32 v117, v74, v75
	v_cvt_pk_bf16_f32 v118, v76, v77
	v_cvt_pk_bf16_f32 v119, v78, v79
	s_waitcnt lgkmcnt(4)
	v_mfma_f32_32x32x16_bf16 v[48:63], v[168:171], v[160:163], v[48:63]
	v_add_f32_e32 v95, v111, v95
	v_add_f32_e32 v231, v231, v95
	s_waitcnt lgkmcnt(4)
	s_barrier
	ds_read_b128 v[188:191], v187 offset:45056
	ds_read_b128 v[168:171], v187 offset:45088
	s_waitcnt lgkmcnt(5)
	v_mfma_f32_32x32x16_bf16 v[16:31], v[128:131], v[112:115], v[16:31]
	ds_read_b128 v[220:223], v187 offset:45120
	s_waitcnt vmcnt(0)
	ds_write_b128 v211, v[176:179] offset:0
	s_and_saveexec_b64 s[42:43], s[36:37]
	s_cbranch_execz .Lattn_fx_w8
	ds_write_b128 v186, v[172:175] offset:0
; template <bool FIXED> __device__ __forceinline__ void attn_unit(unsigned char* ws, LAS unsigned char* lds, int b, int h, int qb, const int tid, const float sbound) {
;     ...
;     if constexpr (FIXED) { for (int kt = 0; kt < SEQ / 64; kt += 2) { ATT_STEP_FIXED(pA0, pA1, pB0, pB1, kt); ATT_STEP_FIXED(pB0, pB1, pA0, pA1, kt + 1); }
.Lattn_fx_w8:
	s_or_b64 exec, exec, s[42:43]
	ds_write_b128 v208, v[180:183] offset:13312
	v_exp_f32_e32 v48, v48
	v_exp_f32_e32 v49, v49
	v_exp_f32_e32 v50, v50
	s_waitcnt lgkmcnt(7)
	v_mfma_f32_32x32x16_bf16 v[32:47], v[132:135], v[112:115], v[32:47]
	ds_read_b128 v[128:131], v187 offset:45152
	global_load_dwordx4 v[176:179], v212, s[6:7]
	s_and_saveexec_b64 s[42:43], s[36:37]
	s_cbranch_execz .Lattn_fx_g9
	global_load_dwordx4 v[172:175], v214, s[6:7]
.Lattn_fx_g9:
	s_or_b64 exec, exec, s[42:43]
	global_load_dwordx4 v[180:183], v204, s[40:41]
	s_add_u32 s6, s6, 0x18000
	s_addc_u32 s7, s7, 0
	s_add_u32 s40, s40, 0x80
	s_addc_u32 s41, s41, 0
	v_exp_f32_e32 v51, v51
	v_exp_f32_e32 v52, v52
	v_exp_f32_e32 v53, v53
	s_waitcnt lgkmcnt(7)
	v_mfma_f32_32x32x16_bf16 v[16:31], v[136:139], v[116:119], v[16:31]
	ds_read_b128 v[132:135], v187 offset:45184
	v_exp_f32_e32 v54, v54
	v_exp_f32_e32 v55, v55
	v_cvt_pk_bf16_f32 v120, v48, v49
	v_cvt_pk_bf16_f32 v121, v50, v51
	s_waitcnt lgkmcnt(7)
	v_mfma_f32_32x32x16_bf16 v[32:47], v[140:143], v[116:119], v[32:47]
	ds_read_b128 v[136:139], v187 offset:45216
	v_cvt_pk_bf16_f32 v122, v52, v53
	v_cvt_pk_bf16_f32 v123, v54, v55
	v_exp_f32_e32 v56, v56
	v_exp_f32_e32 v57, v57
	s_waitcnt lgkmcnt(7)
	v_mfma_f32_32x32x16_bf16 v[96:111], v[188:191], v[164:167], v[0:15]
	ds_read_b128 v[140:143], v209 offset:35904
	v_exp_f32_e32 v58, v58
	v_exp_f32_e32 v59, v59
	v_add_f32_e32 v48, v64, v48
	v_add_f32_e32 v244, v244, v48
	s_waitcnt lgkmcnt(7)
	v_mfma_f32_32x32x16_bf16 v[96:111], v[168:171], v[144:147], v[96:111]
	ds_read_b128 v[188:191], v209 offset:40512
	v_exp_f32_e32 v60, v60
	v_exp_f32_e32 v61, v61
	v_add_f32_e32 v49, v65, v49
	v_add_f32_e32 v245, v245, v49
	s_waitcnt lgkmcnt(7)
	v_mfma_f32_32x32x16_bf16 v[96:111], v[220:223], v[148:151], v[96:111]
	ds_read_b128 v[168:171], v187 offset:51712
	v_exp_f32_e32 v62, v62
	v_exp_f32_e32 v63, v63
	v_add_f32_e32 v50, v66, v50
	v_add_f32_e32 v242, v242, v50
	s_waitcnt lgkmcnt(5)
	v_mfma_f32_32x32x16_bf16 v[96:111], v[128:131], v[152:155], v[96:111]
	ds_read_b128 v[220:223], v187 offset:51744
	v_cvt_pk_bf16_f32 v124, v56, v57
	v_cvt_pk_bf16_f32 v125, v58, v59
	v_cvt_pk_bf16_f32 v126, v60, v61
	v_cvt_pk_bf16_f32 v127, v62, v63
	v_add_f32_e32 v51, v67, v51
	v_add_f32_e32 v243, v243, v51
	s_waitcnt lgkmcnt(5)
	v_mfma_f32_32x32x16_bf16 v[96:111], v[132:135], v[156:159], v[96:111]
	ds_read_b128 v[128:131], v187 offset:51776
	v_add_f32_e32 v52, v68, v52
	v_add_f32_e32 v240, v240, v52
	v_add_f32_e32 v53, v69, v53
	v_add_f32_e32 v241, v241, v53
	v_add_f32_e32 v54, v70, v54
	v_add_f32_e32 v238, v238, v54
	s_waitcnt lgkmcnt(5)
	v_mfma_f32_32x32x16_bf16 v[96:111], v[136:139], v[160:163], v[96:111]
	ds_read_b128 v[132:135], v209 offset:35936
	v_add_f32_e32 v55, v71, v55
	v_add_f32_e32 v239, v239, v55
	v_add_f32_e32 v56, v72, v56
	v_add_f32_e32 v236, v236, v56
	v_add_f32_e32 v57, v73, v57
	v_add_f32_e32 v237, v237, v57
	s_waitcnt lgkmcnt(5)
	v_mfma_f32_32x32x16_bf16 v[16:31], v[140:143], v[120:123], v[16:31]
	ds_read_b128 v[136:139], v209 offset:40544
	v_add_f32_e32 v58, v74, v58
	v_add_f32_e32 v234, v234, v58
	v_add_f32_e32 v59, v75, v59
	v_add_f32_e32 v235, v235, v59
	v_add_f32_e32 v60, v76, v60
	v_add_f32_e32 v232, v232, v60
	s_waitcnt lgkmcnt(5)
	v_mfma_f32_32x32x16_bf16 v[32:47], v[188:191], v[120:123], v[32:47]
	ds_read_b128 v[140:143], v187 offset:51808
	v_add_f32_e32 v61, v77, v61
	v_add_f32_e32 v233, v233, v61
	v_add_f32_e32 v62, v78, v62
	v_add_f32_e32 v230, v230, v62
	s_waitcnt lgkmcnt(5)
	v_mfma_f32_32x32x16_bf16 v[80:95], v[168:171], v[164:167], v[0:15]
	ds_read_b128 v[188:191], v187 offset:51840
	v_exp_f32_e32 v96, v96
	v_exp_f32_e32 v97, v97
	v_exp_f32_e32 v98, v98
	s_waitcnt lgkmcnt(5)
	v_mfma_f32_32x32x16_bf16 v[80:95], v[220:223], v[144:147], v[80:95]
	ds_read_b128 v[168:171], v187 offset:51872
	v_exp_f32_e32 v99, v99
	v_exp_f32_e32 v100, v100
	v_exp_f32_e32 v101, v101
	s_waitcnt lgkmcnt(5)
	v_mfma_f32_32x32x16_bf16 v[80:95], v[128:131], v[148:151], v[80:95]
	ds_read_b128 v[128:131], v209 offset:58368
	v_exp_f32_e32 v102, v102
	v_exp_f32_e32 v103, v103
	v_cvt_pk_bf16_f32 v112, v96, v97
	v_cvt_pk_bf16_f32 v113, v98, v99
	s_waitcnt lgkmcnt(5)
	v_mfma_f32_32x32x16_bf16 v[16:31], v[132:135], v[124:127], v[16:31]
	ds_read_b128 v[132:135], v209 offset:62976
	v_cvt_pk_bf16_f32 v114, v100, v101
	v_cvt_pk_bf16_f32 v115, v102, v103
	v_exp_f32_e32 v104, v104
	v_exp_f32_e32 v105, v105
	s_waitcnt lgkmcnt(5)
	v_mfma_f32_32x32x16_bf16 v[32:47], v[136:139], v[124:127], v[32:47]
	ds_read_b128 v[136:139], v209 offset:58400
	v_exp_f32_e32 v106, v106
	v_exp_f32_e32 v107, v107
	v_exp_f32_e32 v108, v108
	s_waitcnt lgkmcnt(5)
	v_mfma_f32_32x32x16_bf16 v[80:95], v[140:143], v[152:155], v[80:95]
	ds_read_b128 v[140:143], v209 offset:63008
	v_exp_f32_e32 v109, v109
	v_exp_f32_e32 v110, v110
	v_exp_f32_e32 v111, v111
	s_waitcnt lgkmcnt(5)
	v_mfma_f32_32x32x16_bf16 v[80:95], v[188:191], v[156:159], v[80:95]
	v_cvt_pk_bf16_f32 v116, v104, v105
	v_cvt_pk_bf16_f32 v117, v106, v107
	v_cvt_pk_bf16_f32 v118, v108, v109
	v_cvt_pk_bf16_f32 v119, v110, v111
	s_waitcnt lgkmcnt(4)
	v_mfma_f32_32x32x16_bf16 v[80:95], v[168:171], v[160:163], v[80:95]
	v_add_f32_e32 v63, v79, v63
	v_add_f32_e32 v231, v231, v63
	s_waitcnt lgkmcnt(4)
	s_barrier
	ds_read_b128 v[188:191], v187 offset:0
	ds_read_b128 v[168:171], v187 offset:32
	s_waitcnt lgkmcnt(5)
	v_mfma_f32_32x32x16_bf16 v[16:31], v[128:131], v[112:115], v[16:31]
	ds_read_b128 v[220:223], v187 offset:64
	s_waitcnt vmcnt(0)
	ds_write_b128 v211, v[176:179] offset:22528
	s_and_saveexec_b64 s[42:43], s[36:37]
	s_cbranch_execz .Lattn_fx_w10
	ds_write_b128 v186, v[172:175] offset:22528
.Lattn_fx_w10:
	s_or_b64 exec, exec, s[42:43]
	ds_write_b128 v208, v[180:183] offset:35840
	v_exp_f32_e32 v80, v80
	v_exp_f32_e32 v81, v81
	v_exp_f32_e32 v82, v82
	s_waitcnt lgkmcnt(7)
	v_mfma_f32_32x32x16_bf16 v[32:47], v[132:135], v[112:115], v[32:47]
	ds_read_b128 v[128:131], v187 offset:96
	s_cmp_eq_u32 s14, 20
	s_cbranch_scc1 .Lattn_fx_skipld
	global_load_dwordx4 v[176:179], v212, s[6:7]
	s_and_saveexec_b64 s[42:43], s[36:37]
	s_cbranch_execz .Lattn_fx_g11
	global_load_dwordx4 v[172:175], v214, s[6:7]

; template <bool FIXED> __device__ __forceinline__ void attn_unit(unsigned char* ws, LAS unsigned char* lds, int b, int h, int qb, const int tid, const float sbound) {
;     ...
;     if constexpr (FIXED) { for (int kt = 0; kt < SEQ / 64; kt += 2) { ATT_STEP_FIXED(pA0, pA1, pB0, pB1, kt); ATT_STEP_FIXED(pB0, pB1, pA0, pA1, kt + 1); }
.Lattn_fx_skipld:
	v_exp_f32_e32 v83, v83
	v_exp_f32_e32 v84, v84
	v_exp_f32_e32 v85, v85
	s_waitcnt lgkmcnt(7)
	v_mfma_f32_32x32x16_bf16 v[16:31], v[136:139], v[116:119], v[16:31]
	ds_read_b128 v[132:135], v187 offset:128
	v_exp_f32_e32 v86, v86
	v_exp_f32_e32 v87, v87
	v_cvt_pk_bf16_f32 v120, v80, v81
	v_cvt_pk_bf16_f32 v121, v82, v83
	s_waitcnt lgkmcnt(7)
	v_mfma_f32_32x32x16_bf16 v[32:47], v[140:143], v[116:119], v[32:47]
	ds_read_b128 v[136:139], v187 offset:160
	v_cvt_pk_bf16_f32 v122, v84, v85
	v_cvt_pk_bf16_f32 v123, v86, v87
	v_exp_f32_e32 v88, v88
	v_exp_f32_e32 v89, v89
	s_waitcnt lgkmcnt(7)
	v_mfma_f32_32x32x16_bf16 v[64:79], v[188:191], v[164:167], v[0:15]
	ds_read_b128 v[140:143], v209 offset:58432
	v_exp_f32_e32 v90, v90
	v_exp_f32_e32 v91, v91
	v_add_f32_e32 v80, v96, v80
	v_add_f32_e32 v244, v244, v80
	s_waitcnt lgkmcnt(7)
	v_mfma_f32_32x32x16_bf16 v[64:79], v[168:171], v[144:147], v[64:79]
	ds_read_b128 v[188:191], v209 offset:63040
	v_exp_f32_e32 v92, v92
	v_exp_f32_e32 v93, v93
	v_add_f32_e32 v81, v97, v81
	v_add_f32_e32 v245, v245, v81
	s_waitcnt lgkmcnt(7)
	v_mfma_f32_32x32x16_bf16 v[64:79], v[220:223], v[148:151], v[64:79]
	ds_read_b128 v[168:171], v187 offset:6656
	v_exp_f32_e32 v94, v94
	v_exp_f32_e32 v95, v95
	v_add_f32_e32 v82, v98, v82
	v_add_f32_e32 v242, v242, v82
	s_waitcnt lgkmcnt(5)
	v_mfma_f32_32x32x16_bf16 v[64:79], v[128:131], v[152:155], v[64:79]
	ds_read_b128 v[220:223], v187 offset:6688
	v_cvt_pk_bf16_f32 v124, v88, v89
	v_cvt_pk_bf16_f32 v125, v90, v91
	v_cvt_pk_bf16_f32 v126, v92, v93
	v_cvt_pk_bf16_f32 v127, v94, v95
	v_add_f32_e32 v83, v99, v83
	v_add_f32_e32 v243, v243, v83
	s_waitcnt lgkmcnt(5)
	v_mfma_f32_32x32x16_bf16 v[64:79], v[132:135], v[156:159], v[64:79]
	ds_read_b128 v[128:131], v187 offset:6720
	v_add_f32_e32 v84, v100, v84
	v_add_f32_e32 v240, v240, v84
	v_add_f32_e32 v85, v101, v85
	v_add_f32_e32 v241, v241, v85
	v_add_f32_e32 v86, v102, v86
	v_add_f32_e32 v238, v238, v86
	s_waitcnt lgkmcnt(5)
	v_mfma_f32_32x32x16_bf16 v[64:79], v[136:139], v[160:163], v[64:79]
	ds_read_b128 v[132:135], v209 offset:58464
	v_add_f32_e32 v87, v103, v87
	v_add_f32_e32 v239, v239, v87
	v_add_f32_e32 v88, v104, v88
	v_add_f32_e32 v236, v236, v88
	v_add_f32_e32 v89, v105, v89
	v_add_f32_e32 v237, v237, v89
	s_waitcnt lgkmcnt(5)
	v_mfma_f32_32x32x16_bf16 v[16:31], v[140:143], v[120:123], v[16:31]
	ds_read_b128 v[136:139], v209 offset:63072
	v_add_f32_e32 v90, v106, v90
	v_add_f32_e32 v234, v234, v90
	v_add_f32_e32 v91, v107, v91
	v_add_f32_e32 v235, v235, v91
	v_add_f32_e32 v92, v108, v92
	v_add_f32_e32 v232, v232, v92
	s_waitcnt lgkmcnt(5)
	v_mfma_f32_32x32x16_bf16 v[32:47], v[188:191], v[120:123], v[32:47]
	ds_read_b128 v[140:143], v187 offset:6752
	v_add_f32_e32 v93, v109, v93
	v_add_f32_e32 v233, v233, v93
	v_add_f32_e32 v94, v110, v94
	v_add_f32_e32 v230, v230, v94
	s_waitcnt lgkmcnt(5)
	v_mfma_f32_32x32x16_bf16 v[48:63], v[168:171], v[164:167], v[0:15]
	ds_read_b128 v[188:191], v187 offset:6784
	v_exp_f32_e32 v64, v64
	v_exp_f32_e32 v65, v65
	v_exp_f32_e32 v66, v66
	s_waitcnt lgkmcnt(5)
	v_mfma_f32_32x32x16_bf16 v[48:63], v[220:223], v[144:147], v[48:63]
	ds_read_b128 v[168:171], v187 offset:6816
	v_exp_f32_e32 v67, v67
	v_exp_f32_e32 v68, v68
	v_exp_f32_e32 v69, v69
	s_waitcnt lgkmcnt(5)
	v_mfma_f32_32x32x16_bf16 v[48:63], v[128:131], v[148:151], v[48:63]
	ds_read_b128 v[128:131], v209 offset:13312
	v_exp_f32_e32 v70, v70
	v_exp_f32_e32 v71, v71
	v_cvt_pk_bf16_f32 v112, v64, v65
	v_cvt_pk_bf16_f32 v113, v66, v67
	s_waitcnt lgkmcnt(5)
	v_mfma_f32_32x32x16_bf16 v[16:31], v[132:135], v[124:127], v[16:31]
	ds_read_b128 v[132:135], v209 offset:17920
	v_cvt_pk_bf16_f32 v114, v68, v69
	v_cvt_pk_bf16_f32 v115, v70, v71
	v_exp_f32_e32 v72, v72
	v_exp_f32_e32 v73, v73
	s_waitcnt lgkmcnt(5)
	v_mfma_f32_32x32x16_bf16 v[32:47], v[136:139], v[124:127], v[32:47]
	ds_read_b128 v[136:139], v209 offset:13344
	v_exp_f32_e32 v74, v74
	v_exp_f32_e32 v75, v75
	v_exp_f32_e32 v76, v76
	s_waitcnt lgkmcnt(5)
	v_mfma_f32_32x32x16_bf16 v[48:63], v[140:143], v[152:155], v[48:63]
	ds_read_b128 v[140:143], v209 offset:17952
	v_exp_f32_e32 v77, v77
	v_exp_f32_e32 v78, v78
	v_exp_f32_e32 v79, v79
	s_waitcnt lgkmcnt(5)
	v_mfma_f32_32x32x16_bf16 v[48:63], v[188:191], v[156:159], v[48:63]
	v_cvt_pk_bf16_f32 v116, v72, v73
	v_cvt_pk_bf16_f32 v117, v74, v75
	v_cvt_pk_bf16_f32 v118, v76, v77
	v_cvt_pk_bf16_f32 v119, v78, v79
	s_waitcnt lgkmcnt(4)
	v_mfma_f32_32x32x16_bf16 v[48:63], v[168:171], v[160:163], v[48:63]
	v_add_f32_e32 v95, v111, v95
	v_add_f32_e32 v231, v231, v95
	s_waitcnt lgkmcnt(4)
	s_barrier
	s_add_i32 s14, s14, 1
	s_cmp_lt_u32 s14, 21
	s_cbranch_scc1 .Lattn_fx_loop
; template <bool FIXED> __device__ __forceinline__ void attn_unit(unsigned char* ws, LAS unsigned char* lds, int b, int h, int qb, const int tid, const float sbound) {
;     ...
;     if constexpr (FIXED) { for (int kt = 0; kt < SEQ / 64; kt += 2) { ATT_STEP_FIXED(pA0, pA1, pB0, pB1, kt); ATT_STEP_FIXED(pB0, pB1, pA0, pA1, kt + 1); }
	ds_read_b128 v[188:191], v187 offset:22528
	ds_read_b128 v[168:171], v187 offset:22560
	s_waitcnt lgkmcnt(5)
	v_mfma_f32_32x32x16_bf16 v[16:31], v[128:131], v[112:115], v[16:31]
	ds_read_b128 v[220:223], v187 offset:22592
	s_nop 7
	v_exp_f32_e32 v48, v48
	v_exp_f32_e32 v49, v49
	v_exp_f32_e32 v50, v50
	s_waitcnt lgkmcnt(5)
	v_mfma_f32_32x32x16_bf16 v[32:47], v[132:135], v[112:115], v[32:47]
	ds_read_b128 v[128:131], v187 offset:22624
	v_exp_f32_e32 v51, v51
	v_exp_f32_e32 v52, v52
	v_exp_f32_e32 v53, v53
	s_waitcnt lgkmcnt(5)
	v_mfma_f32_32x32x16_bf16 v[16:31], v[136:139], v[116:119], v[16:31]
	ds_read_b128 v[132:135], v187 offset:22656
	v_exp_f32_e32 v54, v54
	v_exp_f32_e32 v55, v55
	v_cvt_pk_bf16_f32 v120, v48, v49
	v_cvt_pk_bf16_f32 v121, v50, v51
	s_waitcnt lgkmcnt(5)
	v_mfma_f32_32x32x16_bf16 v[32:47], v[140:143], v[116:119], v[32:47]
	ds_read_b128 v[136:139], v187 offset:22688
	v_cvt_pk_bf16_f32 v122, v52, v53
	v_cvt_pk_bf16_f32 v123, v54, v55
	v_exp_f32_e32 v56, v56
	v_exp_f32_e32 v57, v57
	s_waitcnt lgkmcnt(5)
	v_mfma_f32_32x32x16_bf16 v[96:111], v[188:191], v[164:167], v[0:15]
	ds_read_b128 v[140:143], v209 offset:13376
	v_exp_f32_e32 v58, v58
	v_exp_f32_e32 v59, v59
	v_add_f32_e32 v48, v64, v48
	v_add_f32_e32 v244, v244, v48
	s_waitcnt lgkmcnt(5)
	v_mfma_f32_32x32x16_bf16 v[96:111], v[168:171], v[144:147], v[96:111]
	ds_read_b128 v[188:191], v209 offset:17984
	v_exp_f32_e32 v60, v60
	v_exp_f32_e32 v61, v61
	v_add_f32_e32 v49, v65, v49
	v_add_f32_e32 v245, v245, v49
	s_waitcnt lgkmcnt(5)
	v_mfma_f32_32x32x16_bf16 v[96:111], v[220:223], v[148:151], v[96:111]
	ds_read_b128 v[168:171], v187 offset:29184
	v_exp_f32_e32 v62, v62
	v_exp_f32_e32 v63, v63
	v_add_f32_e32 v50, v66, v50
	v_add_f32_e32 v242, v242, v50
	s_waitcnt lgkmcnt(5)
	v_mfma_f32_32x32x16_bf16 v[96:111], v[128:131], v[152:155], v[96:111]
	ds_read_b128 v[220:223], v187 offset:29216
	v_cvt_pk_bf16_f32 v124, v56, v57
	v_cvt_pk_bf16_f32 v125, v58, v59
	v_cvt_pk_bf16_f32 v126, v60, v61
	v_cvt_pk_bf16_f32 v127, v62, v63
	v_add_f32_e32 v51, v67, v51
	v_add_f32_e32 v243, v243, v51
	s_waitcnt lgkmcnt(5)
	v_mfma_f32_32x32x16_bf16 v[96:111], v[132:135], v[156:159], v[96:111]
	ds_read_b128 v[128:131], v187 offset:29248
	v_add_f32_e32 v52, v68, v52
	v_add_f32_e32 v240, v240, v52
	v_add_f32_e32 v53, v69, v53
	v_add_f32_e32 v241, v241, v53
	v_add_f32_e32 v54, v70, v54
	v_add_f32_e32 v238, v238, v54
	s_waitcnt lgkmcnt(5)
	v_mfma_f32_32x32x16_bf16 v[96:111], v[136:139], v[160:163], v[96:111]
	ds_read_b128 v[132:135], v209 offset:13408
	v_add_f32_e32 v55, v71, v55
	v_add_f32_e32 v239, v239, v55
	v_add_f32_e32 v56, v72, v56
	v_add_f32_e32 v236, v236, v56
	v_add_f32_e32 v57, v73, v57
	v_add_f32_e32 v237, v237, v57
	s_waitcnt lgkmcnt(5)
	v_mfma_f32_32x32x16_bf16 v[16:31], v[140:143], v[120:123], v[16:31]
	ds_read_b128 v[136:139], v209 offset:18016
	v_add_f32_e32 v58, v74, v58
	v_add_f32_e32 v234, v234, v58
	v_add_f32_e32 v59, v75, v59
	v_add_f32_e32 v235, v235, v59
	v_add_f32_e32 v60, v76, v60
	v_add_f32_e32 v232, v232, v60
	s_waitcnt lgkmcnt(5)
	v_mfma_f32_32x32x16_bf16 v[32:47], v[188:191], v[120:123], v[32:47]
	ds_read_b128 v[140:143], v187 offset:29280
	v_add_f32_e32 v61, v77, v61
	v_add_f32_e32 v233, v233, v61
	v_add_f32_e32 v62, v78, v62
	v_add_f32_e32 v230, v230, v62
	s_waitcnt lgkmcnt(5)
	v_mfma_f32_32x32x16_bf16 v[80:95], v[168:171], v[164:167], v[0:15]
	ds_read_b128 v[188:191], v187 offset:29312
	v_exp_f32_e32 v96, v96
	v_exp_f32_e32 v97, v97
	v_exp_f32_e32 v98, v98
	s_waitcnt lgkmcnt(5)
	v_mfma_f32_32x32x16_bf16 v[80:95], v[220:223], v[144:147], v[80:95]
	ds_read_b128 v[168:171], v187 offset:29344
	v_exp_f32_e32 v99, v99
	v_exp_f32_e32 v100, v100
	v_exp_f32_e32 v101, v101
	s_waitcnt lgkmcnt(5)
	v_mfma_f32_32x32x16_bf16 v[80:95], v[128:131], v[148:151], v[80:95]
	ds_read_b128 v[128:131], v209 offset:35840
	v_exp_f32_e32 v102, v102
	v_exp_f32_e32 v103, v103
	v_cvt_pk_bf16_f32 v112, v96, v97
	v_cvt_pk_bf16_f32 v113, v98, v99
	s_waitcnt lgkmcnt(5)
	v_mfma_f32_32x32x16_bf16 v[16:31], v[132:135], v[124:127], v[16:31]
	ds_read_b128 v[132:135], v209 offset:40448
	v_cvt_pk_bf16_f32 v114, v100, v101
	v_cvt_pk_bf16_f32 v115, v102, v103
	v_exp_f32_e32 v104, v104
	v_exp_f32_e32 v105, v105
	s_waitcnt lgkmcnt(5)
	v_mfma_f32_32x32x16_bf16 v[32:47], v[136:139], v[124:127], v[32:47]
	ds_read_b128 v[136:139], v209 offset:35872
	v_exp_f32_e32 v106, v106
	v_exp_f32_e32 v107, v107
	v_exp_f32_e32 v108, v108
	s_waitcnt lgkmcnt(5)
	v_mfma_f32_32x32x16_bf16 v[80:95], v[140:143], v[152:155], v[80:95]
	ds_read_b128 v[140:143], v209 offset:40480
	v_exp_f32_e32 v109, v109
	v_exp_f32_e32 v110, v110
	v_exp_f32_e32 v111, v111
	s_waitcnt lgkmcnt(5)
	v_mfma_f32_32x32x16_bf16 v[80:95], v[188:191], v[156:159], v[80:95]
	v_cvt_pk_bf16_f32 v116, v104, v105
	v_cvt_pk_bf16_f32 v117, v106, v107
	v_cvt_pk_bf16_f32 v118, v108, v109
	v_cvt_pk_bf16_f32 v119, v110, v111
	s_waitcnt lgkmcnt(4)
	v_mfma_f32_32x32x16_bf16 v[80:95], v[168:171], v[160:163], v[80:95]
	v_add_f32_e32 v63, v79, v63
	v_add_f32_e32 v231, v231, v63
	s_waitcnt lgkmcnt(4)
	s_barrier
; template <bool FIXED> __device__ __forceinline__ void attn_unit(unsigned char* ws, LAS unsigned char* lds, int b, int h, int qb, const int tid, const float sbound) {
;     ...
;     if constexpr (FIXED) { for (int kt = 0; kt < SEQ / 64; kt += 2) { ATT_STEP_FIXED(pA0, pA1, pB0, pB1, kt); ATT_STEP_FIXED(pB0, pB1, pA0, pA1, kt + 1); }
; #pragma unroll
;         for (int r = 0; r < 16; ++r) lsum += lacc[r]; }
	ds_read_b128 v[188:191], v209 offset:35904
	ds_read_b128 v[168:171], v209 offset:40512
	s_waitcnt lgkmcnt(5)
	v_mfma_f32_32x32x16_bf16 v[16:31], v[128:131], v[112:115], v[16:31]
	ds_read_b128 v[220:223], v209 offset:35936
	s_nop 7
	v_exp_f32_e32 v80, v80
	v_exp_f32_e32 v81, v81
	v_exp_f32_e32 v82, v82
	v_exp_f32_e32 v83, v83
	v_exp_f32_e32 v84, v84
	v_exp_f32_e32 v85, v85
	v_exp_f32_e32 v86, v86
	v_exp_f32_e32 v87, v87
	s_waitcnt lgkmcnt(5)
	v_mfma_f32_32x32x16_bf16 v[32:47], v[132:135], v[112:115], v[32:47]
	ds_read_b128 v[128:131], v209 offset:40544
	v_cvt_pk_bf16_f32 v120, v80, v81
	v_cvt_pk_bf16_f32 v121, v82, v83
	v_cvt_pk_bf16_f32 v122, v84, v85
	v_cvt_pk_bf16_f32 v123, v86, v87
	v_exp_f32_e32 v88, v88
	v_exp_f32_e32 v89, v89
	v_exp_f32_e32 v90, v90
	v_exp_f32_e32 v91, v91
	s_waitcnt lgkmcnt(5)
	v_mfma_f32_32x32x16_bf16 v[16:31], v[136:139], v[116:119], v[16:31]
	v_exp_f32_e32 v92, v92
	v_exp_f32_e32 v93, v93
	v_exp_f32_e32 v94, v94
	v_exp_f32_e32 v95, v95
	s_waitcnt lgkmcnt(4)
	v_mfma_f32_32x32x16_bf16 v[32:47], v[140:143], v[116:119], v[32:47]
	v_cvt_pk_bf16_f32 v124, v88, v89
	v_cvt_pk_bf16_f32 v125, v90, v91
	v_cvt_pk_bf16_f32 v126, v92, v93
	v_cvt_pk_bf16_f32 v127, v94, v95
	s_waitcnt lgkmcnt(3)
	v_mfma_f32_32x32x16_bf16 v[16:31], v[188:191], v[120:123], v[16:31]
	v_add_f32_e32 v80, v96, v80
	v_add_f32_e32 v244, v244, v80
	v_add_f32_e32 v81, v97, v81
	v_add_f32_e32 v245, v245, v81
	v_add_f32_e32 v82, v98, v82
	v_add_f32_e32 v242, v242, v82
	v_add_f32_e32 v83, v99, v83
	v_add_f32_e32 v243, v243, v83
	s_waitcnt lgkmcnt(2)
	v_mfma_f32_32x32x16_bf16 v[32:47], v[168:171], v[120:123], v[32:47]
	v_add_f32_e32 v84, v100, v84
	v_add_f32_e32 v240, v240, v84
	v_add_f32_e32 v85, v101, v85
	v_add_f32_e32 v241, v241, v85
	v_add_f32_e32 v86, v102, v86
	v_add_f32_e32 v238, v238, v86
	v_add_f32_e32 v87, v103, v87
	v_add_f32_e32 v239, v239, v87
	s_waitcnt lgkmcnt(1)
	v_mfma_f32_32x32x16_bf16 v[16:31], v[220:223], v[124:127], v[16:31]
	v_add_f32_e32 v88, v104, v88
	v_add_f32_e32 v236, v236, v88
	v_add_f32_e32 v89, v105, v89
	v_add_f32_e32 v237, v237, v89
	v_add_f32_e32 v90, v106, v90
	v_add_f32_e32 v234, v234, v90
	v_add_f32_e32 v91, v107, v91
	v_add_f32_e32 v235, v235, v91
	s_waitcnt lgkmcnt(0)
	v_mfma_f32_32x32x16_bf16 v[32:47], v[128:131], v[124:127], v[32:47]
	v_add_f32_e32 v92, v108, v92
	v_add_f32_e32 v232, v232, v92
	v_add_f32_e32 v93, v109, v93
	v_add_f32_e32 v233, v233, v93
	v_add_f32_e32 v94, v110, v94
	v_add_f32_e32 v230, v230, v94
	v_add_f32_e32 v95, v111, v95
	v_add_f32_e32 v231, v231, v95
	s_waitcnt lgkmcnt(0)
	s_barrier
